# post-hoc softmax rescale threshold lowered from 2^13 to 64 (rescale path exercised on first tiles; smaller probability magnitudes)
# speedup vs baseline: 1.0180x; 1.0045x over previous
; #define LAS __attribute__((address_space(3)))
; DI unsigned pk2(float lo, float hi) { f32x2 v = {lo, hi}; bf16x2_t b = __builtin_convertvector(v, bf16x2_t); return __builtin_bit_cast(unsigned, b); }
; #define MFMA32(a, b, c) __builtin_amdgcn_mfma_f32_32x32x16_bf16((a), (b), (c), 0, 0, 0)
; template <int NK32>
; DI void attn_tile(const LAS unsigned char* Kb, const LAS unsigned char* Vb, int map, int lane, const bf16x8 (&Q)[4], f32x16 (&O)[4], float& m, float& l) {
;     ...
;     float ps = 0.f;
; #pragma unroll
;     for (int kt = 0; kt < NK32; ++kt)
; #pragma unroll
;         for (int i = 0; i < 16; ++i) { const float p = __builtin_amdgcn_exp2f(S[kt][i] - m); S[kt][i] = p; ps += p; }
;     l += ps;
; #pragma unroll
;     for (int sl = 0; sl < 2 * NK32; ++sl) {
;         const int kt = sl >> 1, r0 = 8 * (sl & 1);
;         v4u pu; pu.x = pk2(S[kt][r0 + 0], S[kt][r0 + 1]); pu.y = pk2(S[kt][r0 + 2], S[kt][r0 + 3]); pu.z = pk2(S[kt][r0 + 4], S[kt][r0 + 5]); pu.w = pk2(S[kt][r0 + 6], S[kt][r0 + 7]);
;         const bf16x8 pf = __builtin_bit_cast(bf16x8, pu);
; #pragma unroll
;         for (int dt = 0; dt < 4; ++dt) {
;             const bf16x8 vf = *(const LAS bf16x8*)(Vb + (dt * 32 + r32) * 144 + sl * 32 + hf * 16);
;             O[dt] = MFMA32(vf, pf, O[dt]);
;         }
;     }
.LBB0_1431:
	s_sub_i32 s11, 0x8c00, s10
	v_add_u32_e32 v210, s11, v132
	v_add_u32_e32 v211, s11, v134
	v_add_u32_e32 v212, s11, v136
	v_add_u32_e32 v213, s11, v138
	ds_read_b128 v[232:235], v253 offset:17440
	ds_read_b128 v[236:239], v254 offset:17440
	ds_read_b128 v[240:243], v253 offset:26656
	ds_read_b128 v[244:247], v252 offset:17440
	s_waitcnt lgkmcnt(4)
	v_mfma_f32_32x32x16_bf16 v[48:63], v[214:217], v[164:167], v[48:63]
	v_exp_f32_e32 v156, v88
	v_exp_f32_e32 v157, v89
	v_exp_f32_e32 v158, v90
	v_exp_f32_e32 v159, v91
	v_add_f32_e32 v168, v156, v168
	v_mfma_f32_32x32x16_bf16 v[32:47], v[218:221], v[164:167], v[32:47]
	v_exp_f32_e32 v160, v92
	v_exp_f32_e32 v161, v93
	v_add_f32_e32 v169, v157, v169
	v_add_f32_e32 v168, v158, v168
	v_cvt_pk_bf16_f32 v176, v156, v157
	v_mfma_f32_32x32x16_bf16 v[16:31], v[222:225], v[164:167], v[16:31]
	v_exp_f32_e32 v162, v94
	v_exp_f32_e32 v163, v95
	v_add_f32_e32 v169, v159, v169
	v_add_f32_e32 v168, v160, v168
	v_cvt_pk_bf16_f32 v177, v158, v159
	v_mfma_f32_32x32x16_bf16 v[0:15], v[226:229], v[164:167], v[0:15]
	s_waitcnt vmcnt(3)
	ds_write_b128 v210, v[118:121]
	ds_read_b128 v[214:217], v253 offset:17472
	ds_read_b128 v[218:221], v254 offset:17472
	ds_read_b128 v[222:225], v253 offset:26688
	ds_read_b128 v[226:229], v252 offset:17472
	v_cvt_pk_bf16_f32 v178, v160, v161
	v_cvt_pk_bf16_f32 v179, v162, v163
	v_add_f32_e32 v169, v161, v169
	v_add_f32_e32 v168, v162, v168
	v_add_f32_e32 v169, v163, v169
	s_waitcnt lgkmcnt(5)
	v_mfma_f32_32x32x16_bf16 v[48:63], v[232:235], v[176:179], v[48:63]
	v_exp_f32_e32 v156, v64
	v_exp_f32_e32 v157, v65
	v_exp_f32_e32 v158, v66
	v_exp_f32_e32 v159, v67
	v_add_f32_e32 v168, v156, v168
	v_mfma_f32_32x32x16_bf16 v[32:47], v[236:239], v[176:179], v[32:47]
	v_exp_f32_e32 v160, v68
	v_exp_f32_e32 v161, v69
	v_add_f32_e32 v169, v157, v169
	v_add_f32_e32 v168, v158, v168
	v_cvt_pk_bf16_f32 v164, v156, v157
	v_mfma_f32_32x32x16_bf16 v[16:31], v[240:243], v[176:179], v[16:31]
	s_waitcnt vmcnt(2)
	ds_write_b128 v211, v[114:117] offset:17408
	v_exp_f32_e32 v162, v70
	v_exp_f32_e32 v163, v71
	v_add_f32_e32 v169, v159, v169
	v_add_f32_e32 v168, v160, v168
	v_cvt_pk_bf16_f32 v165, v158, v159
	v_mfma_f32_32x32x16_bf16 v[0:15], v[244:247], v[176:179], v[0:15]
	ds_read_b128 v[232:235], v253 offset:17504
	ds_read_b128 v[236:239], v254 offset:17504
	ds_read_b128 v[240:243], v253 offset:26720
	ds_read_b128 v[244:247], v252 offset:17504
	v_cvt_pk_bf16_f32 v166, v160, v161
	v_cvt_pk_bf16_f32 v167, v162, v163
	v_add_f32_e32 v169, v161, v169
	v_add_f32_e32 v168, v162, v168
	v_add_f32_e32 v169, v163, v169
	s_waitcnt lgkmcnt(5)
	v_mfma_f32_32x32x16_bf16 v[48:63], v[214:217], v[164:167], v[48:63]
	v_exp_f32_e32 v156, v72
	v_exp_f32_e32 v157, v73
	v_exp_f32_e32 v158, v74
	v_exp_f32_e32 v159, v75
	v_add_f32_e32 v168, v156, v168
	v_mfma_f32_32x32x16_bf16 v[32:47], v[218:221], v[164:167], v[32:47]
	s_waitcnt vmcnt(1)
	ds_write_b128 v212, v[126:129]
	v_exp_f32_e32 v160, v76
	v_exp_f32_e32 v161, v77
	v_add_f32_e32 v169, v157, v169
	v_add_f32_e32 v168, v158, v168
	v_cvt_pk_bf16_f32 v176, v156, v157
	v_mfma_f32_32x32x16_bf16 v[16:31], v[222:225], v[164:167], v[16:31]
	v_exp_f32_e32 v162, v78
	v_exp_f32_e32 v163, v79
	v_add_f32_e32 v169, v159, v169
	v_add_f32_e32 v168, v160, v168
	v_cvt_pk_bf16_f32 v177, v158, v159
	v_mfma_f32_32x32x16_bf16 v[0:15], v[226:229], v[164:167], v[0:15]
	v_cvt_pk_bf16_f32 v178, v160, v161
	v_cvt_pk_bf16_f32 v179, v162, v163
	v_add_f32_e32 v169, v161, v169
	v_add_f32_e32 v168, v162, v168
	v_add_f32_e32 v169, v163, v169
	s_waitcnt lgkmcnt(1)
	v_mfma_f32_32x32x16_bf16 v[48:63], v[232:235], v[176:179], v[48:63]
	s_waitcnt vmcnt(0)
	ds_write_b128 v213, v[122:125] offset:17408
	v_mfma_f32_32x32x16_bf16 v[32:47], v[236:239], v[176:179], v[32:47]
	v_mfma_f32_32x32x16_bf16 v[16:31], v[240:243], v[176:179], v[16:31]
	v_mfma_f32_32x32x16_bf16 v[0:15], v[244:247], v[176:179], v[0:15]
	v_add_f32_e32 v168, v168, v169
	v_add_f32_e32 v133, v133, v168
	v_cmp_lt_f32_e32 vcc, 0x42800000, v168
	s_cbranch_vccnz .Lpost_resc
